# residual-GEMM (FFN-out, pool, O-proj) K-loop LDS-DMA loads also converted to scalar base + 32-bit lane offset
# speedup vs baseline: 1.0123x; 1.0003x over previous
.LBB0_194:
	s_add_i32 s27, s30, 2
	s_add_u32 s33, s34, s100
	s_addc_u32 s31, s35, 0
	s_cmp_eq_u32 s90, s30
	s_cselect_b32 s31, s15, s31
	s_cselect_b32 s30, s14, s33
	s_cselect_b32 s45, s29, s4
	s_cselect_b32 s44, s28, s1
	s_add_i32 s33, 0, 0x14000
	v_add_u32_e32 v142, s62, v240
	v_add_u32_e32 v158, s33, v240
	ds_read_b128 v[130:133], v142
	ds_read_b128 v[134:137], v142 offset:1024
	ds_read_b128 v[138:141], v142 offset:2048
	ds_read_b128 v[142:145], v142 offset:3072
	ds_read_b128 v[146:149], v158
	ds_read_b128 v[150:153], v158 offset:1024
	ds_read_b128 v[154:157], v158 offset:2048
	ds_read_b128 v[158:161], v158 offset:3072
	s_add_i32 m0, s82, 0xc000
	ds_read_b128 v[162:165], v242
	ds_read_b128 v[166:169], v242 offset:1024
	ds_read_b128 v[170:173], v242 offset:2048
	ds_read_b128 v[174:177], v242 offset:3072
	ds_read_b128 v[178:181], v242 offset:4096
	ds_read_b128 v[182:185], v242 offset:5120
	ds_read_b128 v[186:189], v242 offset:6144
	ds_read_b128 v[208:211], v242 offset:7168
	global_load_lds_dwordx4 v204, s[34:35]
	s_add_i32 m0, s82, 0xe000
	s_nop 0
	global_load_lds_dwordx4 v206, s[34:35]
	s_waitcnt vmcnt(8)
	s_waitcnt lgkmcnt(0)
	s_barrier
	s_setprio 1
	s_waitcnt lgkmcnt(0)
	v_mfma_f32_16x16x32_bf16 v[126:129], v[130:133], v[162:165], v[126:129]
	v_mfma_f32_16x16x32_bf16 v[122:125], v[138:141], v[162:165], v[122:125]
	v_mfma_f32_16x16x32_bf16 v[110:113], v[130:133], v[170:173], v[110:113]
	v_mfma_f32_16x16x32_bf16 v[98:101], v[138:141], v[170:173], v[98:101]
	v_mfma_f32_16x16x32_bf16 v[94:97], v[130:133], v[178:181], v[94:97]
	v_mfma_f32_16x16x32_bf16 v[82:85], v[138:141], v[178:181], v[82:85]
	v_mfma_f32_16x16x32_bf16 v[78:81], v[130:133], v[186:189], v[78:81]
	v_mfma_f32_16x16x32_bf16 v[66:69], v[138:141], v[186:189], v[66:69]
	v_mfma_f32_16x16x32_bf16 v[126:129], v[134:137], v[166:169], v[126:129]
	v_mfma_f32_16x16x32_bf16 v[122:125], v[142:145], v[166:169], v[122:125]
	v_mfma_f32_16x16x32_bf16 v[110:113], v[134:137], v[174:177], v[110:113]
	v_mfma_f32_16x16x32_bf16 v[98:101], v[142:145], v[174:177], v[98:101]
	v_mfma_f32_16x16x32_bf16 v[94:97], v[134:137], v[182:185], v[94:97]
	v_mfma_f32_16x16x32_bf16 v[82:85], v[142:145], v[182:185], v[82:85]
	v_mfma_f32_16x16x32_bf16 v[78:81], v[134:137], v[208:211], v[78:81]
	v_mfma_f32_16x16x32_bf16 v[66:69], v[142:145], v[208:211], v[66:69]
	s_setprio 0
	s_setprio 1
	v_mfma_f32_16x16x32_bf16 v[118:121], v[146:149], v[162:165], v[118:121]
	v_mfma_f32_16x16x32_bf16 v[114:117], v[154:157], v[162:165], v[114:117]
	v_mfma_f32_16x16x32_bf16 v[106:109], v[146:149], v[170:173], v[106:109]
	v_mfma_f32_16x16x32_bf16 v[102:105], v[154:157], v[170:173], v[102:105]
	v_mfma_f32_16x16x32_bf16 v[90:93], v[146:149], v[178:181], v[90:93]
	v_mfma_f32_16x16x32_bf16 v[86:89], v[154:157], v[178:181], v[86:89]
	v_mfma_f32_16x16x32_bf16 v[74:77], v[146:149], v[186:189], v[74:77]
	v_mfma_f32_16x16x32_bf16 v[70:73], v[154:157], v[186:189], v[70:73]
	v_mfma_f32_16x16x32_bf16 v[118:121], v[150:153], v[166:169], v[118:121]
	v_mfma_f32_16x16x32_bf16 v[114:117], v[158:161], v[166:169], v[114:117]
	v_mfma_f32_16x16x32_bf16 v[106:109], v[150:153], v[174:177], v[106:109]
	v_mfma_f32_16x16x32_bf16 v[102:105], v[158:161], v[174:177], v[102:105]
	v_mfma_f32_16x16x32_bf16 v[90:93], v[150:153], v[182:185], v[90:93]
	v_mfma_f32_16x16x32_bf16 v[86:89], v[158:161], v[182:185], v[86:89]
	v_mfma_f32_16x16x32_bf16 v[74:77], v[150:153], v[208:211], v[74:77]
	v_mfma_f32_16x16x32_bf16 v[70:73], v[158:161], v[208:211], v[70:73]
	s_setprio 0
	s_barrier
	s_add_i32 s46, s62, s52
	s_mov_b32 m0, s46
	ds_read_b128 v[162:165], v242 offset:16384
	ds_read_b128 v[166:169], v242 offset:17408
	ds_read_b128 v[170:173], v242 offset:18432
	ds_read_b128 v[174:177], v242 offset:19456
	ds_read_b128 v[178:181], v242 offset:20480
	ds_read_b128 v[182:185], v242 offset:21504
	ds_read_b128 v[186:189], v242 offset:22528
	ds_read_b128 v[208:211], v242 offset:23552
	global_load_lds_dwordx4 v48, s[44:45]
	s_add_i32 m0, s46, 0x2000
	s_add_i32 s33, s33, s52
	global_load_lds_dwordx4 v198, s[44:45]
	s_add_u32 s44, s44, s41
	s_addc_u32 s45, s45, 0
	s_mov_b32 m0, s33
	s_nop 0
	global_load_lds_dwordx4 v48, s[44:45]
	s_add_i32 m0, s33, 0x2000
	s_nop 0
	global_load_lds_dwordx4 v198, s[44:45]
	s_mov_b32 m0, s82
	s_nop 0
	global_load_lds_dwordx4 v202, s[30:31]
	s_mov_b32 m0, s83
	s_nop 0
	global_load_lds_dwordx4 v200, s[30:31]
	s_waitcnt vmcnt(8)
	s_waitcnt lgkmcnt(0)
	s_barrier
	s_setprio 1
	s_waitcnt lgkmcnt(0)
	v_mfma_f32_16x16x32_bf16 v[62:65], v[130:133], v[162:165], v[62:65]
	v_mfma_f32_16x16x32_bf16 v[50:53], v[138:141], v[162:165], v[50:53]
	v_mfma_f32_16x16x32_bf16 v[44:47], v[130:133], v[170:173], v[44:47]
	v_mfma_f32_16x16x32_bf16 v[32:35], v[138:141], v[170:173], v[32:35]
	v_mfma_f32_16x16x32_bf16 v[28:31], v[130:133], v[178:181], v[28:31]
	v_mfma_f32_16x16x32_bf16 v[16:19], v[138:141], v[178:181], v[16:19]
	v_mfma_f32_16x16x32_bf16 v[12:15], v[130:133], v[186:189], v[12:15]
	v_mfma_f32_16x16x32_bf16 v[0:3], v[138:141], v[186:189], v[0:3]
	v_mfma_f32_16x16x32_bf16 v[62:65], v[134:137], v[166:169], v[62:65]
	v_mfma_f32_16x16x32_bf16 v[50:53], v[142:145], v[166:169], v[50:53]
	v_mfma_f32_16x16x32_bf16 v[44:47], v[134:137], v[174:177], v[44:47]
	v_mfma_f32_16x16x32_bf16 v[32:35], v[142:145], v[174:177], v[32:35]
	v_mfma_f32_16x16x32_bf16 v[28:31], v[134:137], v[182:185], v[28:31]
	v_mfma_f32_16x16x32_bf16 v[16:19], v[142:145], v[182:185], v[16:19]
	v_mfma_f32_16x16x32_bf16 v[12:15], v[134:137], v[208:211], v[12:15]
	v_mfma_f32_16x16x32_bf16 v[0:3], v[142:145], v[208:211], v[0:3]
	s_setprio 0
	s_setprio 1
	v_mfma_f32_16x16x32_bf16 v[58:61], v[146:149], v[162:165], v[58:61]
	v_mfma_f32_16x16x32_bf16 v[54:57], v[154:157], v[162:165], v[54:57]
	v_mfma_f32_16x16x32_bf16 v[40:43], v[146:149], v[170:173], v[40:43]
	v_mfma_f32_16x16x32_bf16 v[36:39], v[154:157], v[170:173], v[36:39]
	v_mfma_f32_16x16x32_bf16 v[24:27], v[146:149], v[178:181], v[24:27]
	v_mfma_f32_16x16x32_bf16 v[20:23], v[154:157], v[178:181], v[20:23]
	v_mfma_f32_16x16x32_bf16 v[8:11], v[146:149], v[186:189], v[8:11]
	v_mfma_f32_16x16x32_bf16 v[4:7], v[154:157], v[186:189], v[4:7]
	v_mfma_f32_16x16x32_bf16 v[58:61], v[150:153], v[166:169], v[58:61]
	v_mfma_f32_16x16x32_bf16 v[54:57], v[158:161], v[166:169], v[54:57]
	v_mfma_f32_16x16x32_bf16 v[40:43], v[150:153], v[174:177], v[40:43]
	v_mfma_f32_16x16x32_bf16 v[36:39], v[158:161], v[174:177], v[36:39]
	v_mfma_f32_16x16x32_bf16 v[24:27], v[150:153], v[182:185], v[24:27]
	v_mfma_f32_16x16x32_bf16 v[20:23], v[158:161], v[182:185], v[20:23]
	v_mfma_f32_16x16x32_bf16 v[8:11], v[150:153], v[208:211], v[8:11]
	v_mfma_f32_16x16x32_bf16 v[4:7], v[158:161], v[208:211], v[4:7]
	s_setprio 0
	s_barrier
	s_add_i32 s55, 0, 0x18000
	s_add_i32 s56, 0, 0x1c000
	v_add_u32_e32 v142, s55, v240
	v_add_u32_e32 v158, s56, v240
	ds_read_b128 v[130:133], v142
	ds_read_b128 v[134:137], v142 offset:1024
	ds_read_b128 v[138:141], v142 offset:2048
	ds_read_b128 v[142:145], v142 offset:3072
	ds_read_b128 v[146:149], v158
	ds_read_b128 v[150:153], v158 offset:1024
	ds_read_b128 v[154:157], v158 offset:2048
	ds_read_b128 v[158:161], v158 offset:3072
	s_add_u32 s30, s30, s50
	s_addc_u32 s31, s31, 0
	s_mov_b32 m0, s84
	ds_read_b128 v[162:165], v242 offset:32768
	ds_read_b128 v[166:169], v242 offset:33792
	ds_read_b128 v[170:173], v242 offset:34816
	ds_read_b128 v[174:177], v242 offset:35840
	ds_read_b128 v[178:181], v242 offset:36864
	ds_read_b128 v[182:185], v242 offset:37888
	ds_read_b128 v[186:189], v242 offset:38912
	ds_read_b128 v[208:211], v242 offset:39936
	global_load_lds_dwordx4 v202, s[30:31]
	s_mov_b32 m0, s85
	s_nop 0
	global_load_lds_dwordx4 v200, s[30:31]
	s_waitcnt vmcnt(8)
	s_waitcnt lgkmcnt(0)
	s_barrier
	s_setprio 1
	s_waitcnt lgkmcnt(0)
	v_mfma_f32_16x16x32_bf16 v[126:129], v[130:133], v[162:165], v[126:129]
	v_mfma_f32_16x16x32_bf16 v[122:125], v[138:141], v[162:165], v[122:125]
	v_mfma_f32_16x16x32_bf16 v[110:113], v[130:133], v[170:173], v[110:113]
	v_mfma_f32_16x16x32_bf16 v[98:101], v[138:141], v[170:173], v[98:101]
	v_mfma_f32_16x16x32_bf16 v[94:97], v[130:133], v[178:181], v[94:97]
	v_mfma_f32_16x16x32_bf16 v[82:85], v[138:141], v[178:181], v[82:85]
	v_mfma_f32_16x16x32_bf16 v[78:81], v[130:133], v[186:189], v[78:81]
	v_mfma_f32_16x16x32_bf16 v[66:69], v[138:141], v[186:189], v[66:69]
	v_mfma_f32_16x16x32_bf16 v[126:129], v[134:137], v[166:169], v[126:129]
	v_mfma_f32_16x16x32_bf16 v[122:125], v[142:145], v[166:169], v[122:125]
	v_mfma_f32_16x16x32_bf16 v[110:113], v[134:137], v[174:177], v[110:113]
	v_mfma_f32_16x16x32_bf16 v[98:101], v[142:145], v[174:177], v[98:101]
	v_mfma_f32_16x16x32_bf16 v[94:97], v[134:137], v[182:185], v[94:97]
	v_mfma_f32_16x16x32_bf16 v[82:85], v[142:145], v[182:185], v[82:85]
	v_mfma_f32_16x16x32_bf16 v[78:81], v[134:137], v[208:211], v[78:81]
	v_mfma_f32_16x16x32_bf16 v[66:69], v[142:145], v[208:211], v[66:69]
	s_setprio 0
	s_setprio 1
	v_mfma_f32_16x16x32_bf16 v[118:121], v[146:149], v[162:165], v[118:121]
	v_mfma_f32_16x16x32_bf16 v[114:117], v[154:157], v[162:165], v[114:117]
	v_mfma_f32_16x16x32_bf16 v[106:109], v[146:149], v[170:173], v[106:109]
	v_mfma_f32_16x16x32_bf16 v[102:105], v[154:157], v[170:173], v[102:105]
	v_mfma_f32_16x16x32_bf16 v[90:93], v[146:149], v[178:181], v[90:93]
	v_mfma_f32_16x16x32_bf16 v[86:89], v[154:157], v[178:181], v[86:89]
	v_mfma_f32_16x16x32_bf16 v[74:77], v[146:149], v[186:189], v[74:77]
	v_mfma_f32_16x16x32_bf16 v[70:73], v[154:157], v[186:189], v[70:73]
	v_mfma_f32_16x16x32_bf16 v[118:121], v[150:153], v[166:169], v[118:121]
	v_mfma_f32_16x16x32_bf16 v[114:117], v[158:161], v[166:169], v[114:117]
	v_mfma_f32_16x16x32_bf16 v[106:109], v[150:153], v[174:177], v[106:109]
	v_mfma_f32_16x16x32_bf16 v[102:105], v[158:161], v[174:177], v[102:105]
	v_mfma_f32_16x16x32_bf16 v[90:93], v[150:153], v[182:185], v[90:93]
	v_mfma_f32_16x16x32_bf16 v[86:89], v[158:161], v[182:185], v[86:89]
	v_mfma_f32_16x16x32_bf16 v[74:77], v[150:153], v[208:211], v[74:77]
	v_mfma_f32_16x16x32_bf16 v[70:73], v[158:161], v[208:211], v[70:73]
	s_setprio 0
	s_barrier
	s_add_i32 s46, s55, s52
	s_sub_u32 s68, s44, s41
	s_subb_u32 s69, s45, 0
	s_add_u32 s68, s68, 0x80
	s_addc_u32 s69, s69, 0
	s_mov_b32 m0, s46
	ds_read_b128 v[162:165], v242 offset:49152
	ds_read_b128 v[166:169], v242 offset:50176
	ds_read_b128 v[170:173], v242 offset:51200
	ds_read_b128 v[174:177], v242 offset:52224
	ds_read_b128 v[178:181], v242 offset:53248
	ds_read_b128 v[182:185], v242 offset:54272
	ds_read_b128 v[186:189], v242 offset:55296
	ds_read_b128 v[208:211], v242 offset:56320
	global_load_lds_dwordx4 v48, s[68:69]
	s_add_i32 m0, s46, 0x2000
	s_add_i32 s46, s56, s52
	global_load_lds_dwordx4 v198, s[68:69]
	s_add_u32 s44, s44, 0x80
	s_addc_u32 s45, s45, 0
	s_mov_b32 m0, s46
	s_nop 0
	global_load_lds_dwordx4 v48, s[44:45]
	s_add_i32 m0, s46, 0x2000
	s_nop 0
	global_load_lds_dwordx4 v198, s[44:45]
	s_sub_u32 s68, s30, s50
	s_subb_u32 s69, s31, 0
	s_add_u32 s68, s68, s100
	s_addc_u32 s69, s69, 0
	s_mov_b32 m0, s86
	s_nop 0
	global_load_lds_dwordx4 v202, s[68:69]
	s_mov_b32 m0, s87
	s_nop 0
	global_load_lds_dwordx4 v200, s[68:69]
	s_waitcnt vmcnt(8)
	s_waitcnt lgkmcnt(0)
	s_barrier
	s_setprio 1
	s_waitcnt lgkmcnt(0)
	v_mfma_f32_16x16x32_bf16 v[62:65], v[130:133], v[162:165], v[62:65]
	v_mfma_f32_16x16x32_bf16 v[50:53], v[138:141], v[162:165], v[50:53]
	v_mfma_f32_16x16x32_bf16 v[44:47], v[130:133], v[170:173], v[44:47]
	v_mfma_f32_16x16x32_bf16 v[32:35], v[138:141], v[170:173], v[32:35]
	v_mfma_f32_16x16x32_bf16 v[28:31], v[130:133], v[178:181], v[28:31]
	v_mfma_f32_16x16x32_bf16 v[16:19], v[138:141], v[178:181], v[16:19]
	v_mfma_f32_16x16x32_bf16 v[12:15], v[130:133], v[186:189], v[12:15]
	v_mfma_f32_16x16x32_bf16 v[0:3], v[138:141], v[186:189], v[0:3]
	v_mfma_f32_16x16x32_bf16 v[62:65], v[134:137], v[166:169], v[62:65]
	v_mfma_f32_16x16x32_bf16 v[50:53], v[142:145], v[166:169], v[50:53]
	v_mfma_f32_16x16x32_bf16 v[44:47], v[134:137], v[174:177], v[44:47]
	v_mfma_f32_16x16x32_bf16 v[32:35], v[142:145], v[174:177], v[32:35]
	v_mfma_f32_16x16x32_bf16 v[28:31], v[134:137], v[182:185], v[28:31]
	v_mfma_f32_16x16x32_bf16 v[16:19], v[142:145], v[182:185], v[16:19]
	v_mfma_f32_16x16x32_bf16 v[12:15], v[134:137], v[208:211], v[12:15]
	v_mfma_f32_16x16x32_bf16 v[0:3], v[142:145], v[208:211], v[0:3]
	s_setprio 0
	s_setprio 1
	v_mfma_f32_16x16x32_bf16 v[58:61], v[146:149], v[162:165], v[58:61]
	v_mfma_f32_16x16x32_bf16 v[54:57], v[154:157], v[162:165], v[54:57]
	v_mfma_f32_16x16x32_bf16 v[40:43], v[146:149], v[170:173], v[40:43]
	v_mfma_f32_16x16x32_bf16 v[36:39], v[154:157], v[170:173], v[36:39]
	v_mfma_f32_16x16x32_bf16 v[24:27], v[146:149], v[178:181], v[24:27]
	v_mfma_f32_16x16x32_bf16 v[20:23], v[154:157], v[178:181], v[20:23]
	v_mfma_f32_16x16x32_bf16 v[8:11], v[146:149], v[186:189], v[8:11]
	v_mfma_f32_16x16x32_bf16 v[4:7], v[154:157], v[186:189], v[4:7]
	v_mfma_f32_16x16x32_bf16 v[58:61], v[150:153], v[166:169], v[58:61]
	v_mfma_f32_16x16x32_bf16 v[54:57], v[158:161], v[166:169], v[54:57]
	v_mfma_f32_16x16x32_bf16 v[40:43], v[150:153], v[174:177], v[40:43]
	v_mfma_f32_16x16x32_bf16 v[36:39], v[158:161], v[174:177], v[36:39]
	v_mfma_f32_16x16x32_bf16 v[24:27], v[150:153], v[182:185], v[24:27]
	v_mfma_f32_16x16x32_bf16 v[20:23], v[158:161], v[182:185], v[20:23]
	v_mfma_f32_16x16x32_bf16 v[8:11], v[150:153], v[208:211], v[8:11]
	v_mfma_f32_16x16x32_bf16 v[4:7], v[158:161], v[208:211], v[4:7]
	s_setprio 0
	s_barrier
	s_add_u32 s34, s34, s100
	s_addc_u32 s35, s35, 0
	s_add_u32 s34, s34, s100
	s_addc_u32 s35, s35, 0
	s_add_u32 s1, s1, 0x100
	s_addc_u32 s4, s4, 0
	s_cmp_ge_u32 s27, s89
	s_mov_b32 s30, s27
	s_cbranch_scc0 .LBB0_194
	s_and_b64 vcc, exec, s[24:25]
	s_cbranch_vccz .LBB0_197
	s_barrier
